# ctx attention: next tile's K/V fetched before the current tile's compute via LDS-DMA into a per-wave staging area (the compiler had sunk the prefetch to just before its use)
# baseline (speedup 1.0000x reference)
.LBB0_435:
	s_or_b64 exec, exec, s[0:1]
	s_mov_b64 s[0:1], src_shared_base
	s_add_i32 s0, 0, 0x11fe0
	s_cmp_lg_u32 s0, -1
	s_cselect_b32 s0, s0, 0
	s_cselect_b32 s1, s1, 0
	v_mov_b32_e32 v0, s0
	v_mov_b32_e32 v1, s1
	s_waitcnt lgkmcnt(0)
	s_barrier
	s_waitcnt vmcnt(11)
	flat_load_dword v32, v[0:1] sc0 sc1
	s_waitcnt vmcnt(0)
	v_readlane_b32 s0, v254, 54
	s_waitcnt lgkmcnt(0)
	s_nop 0
	v_cmp_gt_i32_e32 vcc, s0, v32
	s_mov_b64 s[0:1], -1
	s_and_saveexec_b64 s[96:97], vcc
	s_cbranch_execz .LBB0_430
	s_movk_i32 s0, 0x600
	v_cmp_gt_i32_e32 vcc, s0, v32
	s_and_saveexec_b64 s[0:1], vcc
	s_xor_b64 s[0:1], exec, s[0:1]
	v_writelane_b32 v255, s0, 2
	s_nop 1
	v_writelane_b32 v255, s1, 3
	s_cbranch_execz .LBB0_560
	s_movk_i32 s0, 0x500
	v_cmp_gt_i32_e32 vcc, s0, v32
	s_and_saveexec_b64 s[0:1], vcc
	s_xor_b64 s[0:1], exec, s[0:1]
	v_writelane_b32 v255, s0, 4
	s_nop 1
	v_writelane_b32 v255, s1, 5
	s_cbranch_execz .LBB0_551
	s_movk_i32 s0, 0x7f
	v_cmp_lt_i32_e32 vcc, s0, v32
	s_and_saveexec_b64 s[0:1], vcc
	s_xor_b64 s[0:1], exec, s[0:1]
	s_cbranch_execz .LBB0_526
	v_writelane_b32 v255, s0, 6
	v_cmp_lt_u32_e32 vcc, s89, v32
	s_nop 0
	v_writelane_b32 v255, s1, 7
	s_and_saveexec_b64 s[0:1], vcc
	s_xor_b64 s[16:17], exec, s[0:1]
	s_cbranch_execz .LBB0_507
	s_movk_i32 s0, 0x2ff
	v_cmp_lt_u32_e32 vcc, s0, v32
	s_and_saveexec_b64 s[0:1], vcc
	s_xor_b64 s[0:1], exec, s[0:1]
	s_cbranch_execz .LBB0_448
	v_add_u32_e32 v0, 0xfffffd00, v32
	v_mov_b32_e32 v35, v166
	v_lshrrev_b32_e32 v33, 4, v0
	v_bfe_u32 v34, v32, 3, 1
	v_lshlrev_b32_e32 v69, 8, v33
	v_ashrrev_i32_e32 v0, 6, v35
	v_lshl_add_u32 v36, v34, 2, v0
	v_lshlrev_b32_e32 v0, 5, v32
	v_and_b32_e32 v68, 15, v35
	v_and_b32_e32 v70, 0xe0, v0
	v_lshlrev_b32_e32 v48, 6, v36
	v_ashrrev_i32_e32 v49, 31, v48
	v_or3_b32 v2, v70, v68, v69
	v_bfe_u32 v53, v35, 4, 2
	v_lshl_add_u64 v[0:1], v[48:49], 2, s[30:31]
	v_lshlrev_b32_e32 v128, 13, v2
	v_lshl_add_u64 v[16:17], v[0:1], 0, v[128:129]
	v_lshlrev_b32_e32 v128, 5, v53
	s_mov_b64 s[2:3], 0x20000
	v_lshl_add_u64 v[12:13], v[16:17], 0, v[128:129]
	v_lshl_add_u64 v[24:25], v[16:17], 0, s[2:3]
	global_load_dwordx4 v[0:3], v[12:13], off
	global_load_dwordx4 v[4:7], v[12:13], off offset:16
	global_load_dwordx4 v[8:11], v[12:13], off offset:128
	s_nop 0
	global_load_dwordx4 v[12:15], v[12:13], off offset:144
	v_lshl_add_u64 v[20:21], v[24:25], 0, v[128:129]
	global_load_dwordx4 v[16:19], v[20:21], off
	s_nop 0
	global_load_dwordx4 v[20:23], v[20:21], off offset:16
	v_or_b32_e32 v128, 0x80, v128
	v_lshl_add_u64 v[28:29], v[24:25], 0, v[128:129]
	global_load_dwordx4 v[24:27], v[28:29], off
	s_nop 0
	global_load_dwordx4 v[28:31], v[28:29], off offset:16
	s_mov_b32 s2, 0x3e000000
	v_readlane_b32 s68, v254, 8
	v_readlane_b32 s69, v254, 9
	v_ashrrev_i32_e32 v73, 3, v35
	v_and_b32_e32 v58, 7, v35
	v_lshlrev_b32_e32 v128, 8, v34
	v_cmp_eq_u32_e32 vcc, 0, v53
	v_lshrrev_b32_e32 v32, 4, v35
	v_lshl_add_u32 v59, v53, 3, 0
	v_mul_u32_u24_e32 v67, 0x50, v68
	s_mov_b32 s24, 0
	v_add_u32_e32 v79, v59, v67
	v_bfe_u32 v79, v166, 4, 2
	v_bfe_u32 v67, v166, 3, 1
	v_xor_b32_e32 v79, v79, v67
	v_lshlrev_b32_e32 v79, 3, v79
	v_and_b32_e32 v67, 15, v166
	v_lshl_or_b32 v79, v67, 6, v79
	v_readlane_b32 s70, v254, 10
	v_readlane_b32 s71, v254, 11
	v_readlane_b32 s72, v254, 12
	v_readlane_b32 s73, v254, 13
	v_readlane_b32 s74, v254, 14
	v_readlane_b32 s75, v254, 15
	v_readlane_b32 s76, v254, 16
	v_readlane_b32 s77, v254, 17
	v_readlane_b32 s78, v254, 18
	v_readlane_b32 s79, v254, 19
	v_readlane_b32 s80, v254, 20
	v_readlane_b32 s81, v254, 21
	v_readlane_b32 s82, v254, 22
	v_readlane_b32 s83, v254, 23
	s_waitcnt vmcnt(7)
	v_pk_mul_f32 v[0:1], v[0:1], s[2:3] op_sel_hi:[1,0]
	v_pk_mul_f32 v[2:3], v[2:3], s[2:3] op_sel_hi:[1,0]
	s_waitcnt vmcnt(6)
	v_pk_mul_f32 v[4:5], v[4:5], s[2:3] op_sel_hi:[1,0]
	v_pk_mul_f32 v[6:7], v[6:7], s[2:3] op_sel_hi:[1,0]
	s_waitcnt vmcnt(5)
	v_pk_mul_f32 v[8:9], v[8:9], s[2:3] op_sel_hi:[1,0]
	v_pk_mul_f32 v[10:11], v[10:11], s[2:3] op_sel_hi:[1,0]
	s_waitcnt vmcnt(4)
	v_pk_mul_f32 v[14:15], v[14:15], s[2:3] op_sel_hi:[1,0]
	v_pk_mul_f32 v[12:13], v[12:13], s[2:3] op_sel_hi:[1,0]
	v_bfe_u32 v37, v7, 16, 1
	v_bfe_u32 v39, v3, 16, 1
	v_bfe_u32 v41, v5, 16, 1
	v_bfe_u32 v42, v4, 16, 1
	v_bfe_u32 v43, v1, 16, 1
	v_bfe_u32 v44, v0, 16, 1
	v_bfe_u32 v45, v15, 16, 1
	v_bfe_u32 v46, v14, 16, 1
	v_bfe_u32 v47, v11, 16, 1
	v_bfe_u32 v50, v10, 16, 1
	v_bfe_u32 v54, v9, 16, 1
	v_bfe_u32 v55, v8, 16, 1
	s_waitcnt vmcnt(3)
	v_pk_mul_f32 v[16:17], v[16:17], s[2:3] op_sel_hi:[1,0]
	s_waitcnt vmcnt(2)
	v_pk_mul_f32 v[20:21], v[20:21], s[2:3] op_sel_hi:[1,0]
	v_bfe_u32 v51, v13, 16, 1
	v_bfe_u32 v52, v12, 16, 1
	v_add3_u32 v3, v3, v39, s56
	v_add3_u32 v7, v7, v37, s56
	v_add3_u32 v37, v0, v44, s56
	v_add3_u32 v1, v1, v43, s56
	v_add3_u32 v39, v4, v42, s56
	v_add3_u32 v5, v5, v41, s56
	v_add3_u32 v41, v10, v50, s56
	v_add3_u32 v42, v11, v47, s56
	v_add3_u32 v43, v14, v46, s56
	v_add3_u32 v44, v15, v45, s56
	v_add3_u32 v45, v8, v55, s56
	v_add3_u32 v46, v9, v54, s56
	v_bfe_u32 v8, v21, 16, 1
	v_bfe_u32 v9, v20, 16, 1
	v_bfe_u32 v10, v17, 16, 1
	v_bfe_u32 v11, v16, 16, 1
	v_pk_mul_f32 v[18:19], v[18:19], s[2:3] op_sel_hi:[1,0]
	v_pk_mul_f32 v[22:23], v[22:23], s[2:3] op_sel_hi:[1,0]
	v_add3_u32 v47, v12, v52, s56
	v_add3_u32 v51, v13, v51, s56
	v_add3_u32 v56, v16, v11, s56
	v_add3_u32 v57, v17, v10, s56
	v_add3_u32 v20, v20, v9, s56
	v_add3_u32 v21, v21, v8, s56
	s_waitcnt vmcnt(1)
	v_pk_mul_f32 v[8:9], v[24:25], s[2:3] op_sel_hi:[1,0]
	v_pk_mul_f32 v[10:11], v[26:27], s[2:3] op_sel_hi:[1,0]
	s_waitcnt vmcnt(0)
	v_pk_mul_f32 v[12:13], v[28:29], s[2:3] op_sel_hi:[1,0]
	v_pk_mul_f32 v[14:15], v[30:31], s[2:3] op_sel_hi:[1,0]
	v_readlane_b32 s2, v254, 56
	v_bfe_u32 v24, v15, 16, 1
	v_bfe_u32 v29, v8, 16, 1
	v_add_u32_e32 v16, s2, v36
	v_ashrrev_i32_e32 v17, 31, v16
	v_lshl_add_u64 v[16:17], v[16:17], 2, s[68:69]
	global_load_dword v81, v[16:17], off
	v_bfe_u32 v25, v14, 16, 1
	v_bfe_u32 v28, v9, 16, 1
	v_add3_u32 v15, v15, v24, s56
	v_add3_u32 v24, v8, v29, s56
	v_add_u32_e32 v8, v73, v69
	v_add3_u32 v14, v14, v25, s56
	v_add3_u32 v25, v9, v28, s56
	v_ashrrev_i32_e32 v9, 31, v8
	v_mbcnt_lo_u32_b32 v28, -1, 0
	v_bfe_u32 v40, v2, 16, 1
	v_lshlrev_b64 v[8:9], 13, v[8:9]
	v_mbcnt_hi_u32_b32 v28, -1, v28
	v_bfe_u32 v38, v6, 16, 1
	v_add3_u32 v40, v2, v40, s56
	v_bfe_u32 v2, v22, 16, 1
	v_bfe_u32 v4, v19, 16, 1
	v_lshl_add_u64 v[8:9], s[30:31], 0, v[8:9]
	v_and_b32_e32 v30, 64, v28
	v_add3_u32 v38, v6, v38, s56
	v_bfe_u32 v6, v18, 16, 1
	v_add3_u32 v19, v19, v4, s56
	v_add3_u32 v22, v22, v2, s56
	v_lshlrev_b32_e32 v2, 2, v35
	v_lshlrev_b32_e32 v4, 3, v58
	v_lshl_add_u64 v[8:9], v[8:9], 0, v[128:129]
	s_mov_b64 s[2:3], 0xa00
	v_xor_b32_e32 v29, 16, v28
	v_add_u32_e32 v30, 64, v30
	v_add3_u32 v18, v18, v6, s56
	v_cndmask_b32_e64 v50, 0, 1.0, vcc
	v_and_b32_e32 v2, 12, v2
	v_and_b32_e32 v6, 32, v4
	v_lshl_add_u64 v[64:65], v[8:9], 0, s[2:3]
	s_mov_b64 s[2:3], 0x800
	v_cmp_lt_i32_e32 vcc, v29, v30
	v_lshl_add_u64 v[62:63], v[8:9], 0, s[2:3]
	v_or_b32_e32 v9, v6, v2
	v_cndmask_b32_e32 v29, v28, v29, vcc
	v_bfe_u32 v16, v13, 16, 1
	v_bfe_u32 v17, v12, 16, 1
	v_bfe_u32 v8, v35, 4, 3
	v_lshrrev_b32_e32 v9, 3, v9
	v_lshlrev_b32_e32 v72, 2, v29
	v_xor_b32_e32 v29, 32, v28
	v_add3_u32 v12, v12, v17, s56
	v_add3_u32 v13, v13, v16, s56
	v_lshl_add_u32 v16, v73, 7, 0
	v_bitop3_b32 v17, v9, v32, 7 bitop3:0x78
	v_bitop3_b32 v8, v9, v8, 2 bitop3:0x36
	v_cmp_lt_i32_e32 vcc, v29, v30
	v_bfe_u32 v26, v11, 16, 1
	v_lshl_add_u32 v17, v17, 4, v16
	v_lshl_add_u32 v8, v8, 4, v16
	v_readlane_b32 s2, v254, 63
	v_bfe_u32 v16, v35, 1, 3
	v_cndmask_b32_e32 v28, v28, v29, vcc
	v_bfe_u32 v0, v23, 16, 1
	v_bfe_u32 v27, v10, 16, 1
	v_add3_u32 v11, v11, v26, s56
	v_lshlrev_b32_e32 v26, 3, v35
	v_lshl_or_b32 v54, v33, 9, s2
	v_lshlrev_b32_e32 v71, 2, v28
	s_movk_i32 s2, 0x280
	v_bitop3_b32 v28, v32, v16, 3 bitop3:0x6c
	v_bitop3_b32 v16, v53, v16, 4 bitop3:0x36
	v_add3_u32 v23, v23, v0, s56
	v_mov_b32_e32 v0, 0
	v_add3_u32 v10, v10, v27, s56
	v_and_b32_e32 v26, 8, v26
	v_lshlrev_b32_e32 v9, 1, v73
	v_lshl_add_u32 v27, v68, 7, 0
	v_mad_u32_u24 v61, v58, s2, 0
	v_lshlrev_b32_e32 v66, 4, v28
	v_lshlrev_b32_e32 v16, 4, v16
	s_mov_b32 s2, 0x7060302
	v_lshlrev_b32_e32 v52, 6, v34
	v_mov_b32_e32 v55, v129
	v_perm_b32 v31, v7, v38, s2
	v_perm_b32 v29, v3, v40, s2
	v_perm_b32 v30, v5, v39, s2
	v_perm_b32 v28, v1, v37, s2
	v_perm_b32 v35, v44, v43, s2
	v_perm_b32 v33, v42, v41, s2
	v_perm_b32 v34, v51, v47, s2
	v_perm_b32 v32, v46, v45, s2
	v_perm_b32 v39, v23, v22, s2
	v_perm_b32 v37, v19, v18, s2
	v_perm_b32 v38, v21, v20, s2
	v_perm_b32 v36, v57, v56, s2
	v_perm_b32 v47, v15, v14, s2
	v_perm_b32 v45, v11, v10, s2
	v_perm_b32 v46, v13, v12, s2
	v_perm_b32 v44, v25, v24, s2
	v_lshl_add_u64 v[56:57], s[30:31], 0, v[128:129]
	v_lshlrev_b32_e32 v128, 2, v4
	v_lshlrev_b32_e32 v58, 2, v6
	v_lshlrev_b32_e32 v60, 2, v2
	v_add_u32_e32 v74, v17, v26
	v_add_u32_e32 v75, v8, v26
	v_add_u32_e32 v76, v61, v9
	v_and_b32_e32 v76, 7, v166
	v_lshlrev_b32_e32 v76, 9, v76
	v_lshrrev_b32_e32 v77, 5, v166
	v_xor_b32_e32 v77, v77, v166
	v_and_b32_e32 v77, 7, v77
	v_lshl_or_b32 v76, v77, 3, v76
	v_bfe_u32 v77, v166, 3, 2
	v_lshl_or_b32 v76, v77, 1, v76
	v_add_u32_e32 v77, v27, v66
	v_add_u32_e32 v78, v27, v16
	s_waitcnt vmcnt(0)
	v_mov_b32_e32 v80, v81
	v_mov_b32_e32 v1, v0
	v_mov_b32_e32 v2, v0
	v_mov_b32_e32 v3, v0
	v_mov_b32_e32 v4, v0
	v_mov_b32_e32 v5, v0
	v_mov_b32_e32 v6, v0
	v_mov_b32_e32 v7, v0
	v_mov_b32_e32 v8, v0
	v_mov_b32_e32 v9, v0
	v_mov_b32_e32 v10, v0
	v_mov_b32_e32 v11, v0
	v_mov_b32_e32 v12, v0
	v_mov_b32_e32 v13, v0
	v_mov_b32_e32 v14, v0
	v_mov_b32_e32 v15, v0
	v_mov_b32_e32 v16, v0
	v_mov_b32_e32 v17, v0
	v_mov_b32_e32 v18, v0
	v_mov_b32_e32 v19, v0
	v_mov_b32_e32 v20, v0
	v_mov_b32_e32 v21, v0
	v_mov_b32_e32 v22, v0
	v_mov_b32_e32 v23, v0
	v_mov_b32_e32 v24, v0
	v_mov_b32_e32 v25, v0
	v_mov_b32_e32 v26, v0
	v_mov_b32_e32 v27, v0
	v_mov_b32_e32 v40, v0
	v_mov_b32_e32 v41, v0
	v_mov_b32_e32 v42, v0
	v_mov_b32_e32 v43, v0
	v_mov_b32_e32 v51, v50
	v_lshrrev_b32_e32 v61, 6, v166
	v_mov_b32_e32 v59, v129
	v_readfirstlane_b32 s3, v61
	v_lshl_add_u64 v[62:63], v[62:63], 0, v[58:59]
	v_mov_b32_e32 v61, v129
	s_lshl_b32 s3, s3, 12
	v_lshl_add_u64 v[82:83], v[64:65], 0, v[128:129]
	v_lshl_add_u64 v[62:63], v[62:63], 0, v[60:61]
	s_add_i32 m0, s3, 0x3ff0
	s_nop 0
	global_load_lds_dwordx4 v[82:83], off offset:16
	s_add_i32 m0, s3, 0x4400
	s_nop 0
	global_load_lds_dwordx4 v[82:83], off
	s_add_i32 m0, s3, 0x47c0
	s_nop 0
	global_load_lds_dwordx4 v[62:63], off offset:64
	s_add_i32 m0, s3, 0x4c00
	s_nop 0
	global_load_lds_dwordx4 v[62:63], off
	s_branch .LBB0_443
.LBB0_442:
	s_cmp_lg_u32 s24, 8
	s_cbranch_scc0 .Lattn0_nopf
	v_lshrrev_b32_e32 v61, 6, v166
	v_mov_b32_e32 v59, v129
	v_readfirstlane_b32 s3, v61
	v_lshl_add_u64 v[62:63], v[62:63], 0, v[58:59]
	v_mov_b32_e32 v61, v129
	s_lshl_b32 s3, s3, 12
	v_lshl_add_u64 v[82:83], v[64:65], 0, v[128:129]
	v_lshl_add_u64 v[62:63], v[62:63], 0, v[60:61]
	s_add_i32 m0, s3, 0x3ff0
	s_nop 0
	global_load_lds_dwordx4 v[82:83], off offset:16
	s_add_i32 m0, s3, 0x4400
	s_nop 0
	global_load_lds_dwordx4 v[82:83], off
	s_add_i32 m0, s3, 0x47c0
	s_nop 0
	global_load_lds_dwordx4 v[62:63], off offset:64
	s_add_i32 m0, s3, 0x4c00
	s_nop 0
	global_load_lds_dwordx4 v[62:63], off

.LBB0_443:
	s_barrier
	s_mov_b32 s2, s24
	s_add_i32 s24, s24, 1
	s_cmp_lt_u32 s2, 7
	s_cselect_b32 s2, s24, s2
	s_lshl_b32 s3, s2, 5
	s_add_i32 s25, s3, 0xffffff00
	s_cmp_lt_u32 s2, 8
	s_cselect_b32 s3, s3, s25
	s_cmp_gt_u32 s2, 7
	s_waitcnt vmcnt(0)
	v_and_b32_e32 v59, 63, v166
	v_lshrrev_b32_e32 v61, 6, v166
	v_lshlrev_b32_e32 v59, 4, v59
	v_lshl_add_u32 v59, v61, 12, v59
	ds_read_b128 v[64:67], v59 offset:16384
	ds_read_b128 v[82:85], v59 offset:17408
	ds_read_b128 v[86:89], v59 offset:18432
	ds_read_b128 v[90:93], v59 offset:19456
	s_waitcnt lgkmcnt(0)
	v_and_b32_sdwa v62, v93, v170 dst_sel:DWORD dst_unused:UNUSED_PAD src0_sel:WORD_1 src1_sel:DWORD
	v_and_b32_sdwa v63, v91, v170 dst_sel:DWORD dst_unused:UNUSED_PAD src0_sel:WORD_1 src1_sel:DWORD
	v_and_b32_sdwa v59, v92, v170 dst_sel:DWORD dst_unused:UNUSED_PAD src0_sel:WORD_1 src1_sel:DWORD
	v_and_b32_sdwa v61, v90, v170 dst_sel:DWORD dst_unused:UNUSED_PAD src0_sel:WORD_1 src1_sel:DWORD
	v_add3_u32 v62, v93, v62, s56
	v_add3_u32 v63, v91, v63, s56
	v_add3_u32 v61, v90, v61, s56
	v_add3_u32 v59, v92, v59, s56
	v_and_b32_e32 v62, 0xffff0000, v62
	v_and_b32_e32 v90, 0xffff0000, v63
	v_or_b32_sdwa v63, v62, v59 dst_sel:DWORD dst_unused:UNUSED_PAD src0_sel:DWORD src1_sel:WORD_1
	v_or_b32_sdwa v62, v90, v61 dst_sel:DWORD dst_unused:UNUSED_PAD src0_sel:DWORD src1_sel:WORD_1
	ds_write_b64 v74, v[62:63]
	v_and_b32_sdwa v62, v89, v170 dst_sel:DWORD dst_unused:UNUSED_PAD src0_sel:WORD_1 src1_sel:DWORD
	v_and_b32_sdwa v59, v88, v170 dst_sel:DWORD dst_unused:UNUSED_PAD src0_sel:WORD_1 src1_sel:DWORD
	v_and_b32_sdwa v63, v87, v170 dst_sel:DWORD dst_unused:UNUSED_PAD src0_sel:WORD_1 src1_sel:DWORD
	v_add3_u32 v62, v89, v62, s56
	v_and_b32_sdwa v61, v86, v170 dst_sel:DWORD dst_unused:UNUSED_PAD src0_sel:WORD_1 src1_sel:DWORD
	v_add3_u32 v59, v88, v59, s56
	v_add3_u32 v63, v87, v63, s56
	v_and_b32_e32 v62, 0xffff0000, v62
	v_add3_u32 v61, v86, v61, s56
	v_and_b32_e32 v86, 0xffff0000, v63
	v_or_b32_sdwa v63, v62, v59 dst_sel:DWORD dst_unused:UNUSED_PAD src0_sel:DWORD src1_sel:WORD_1
	v_bfe_u32 v59, v82, 16, 1
	v_or_b32_sdwa v62, v86, v61 dst_sel:DWORD dst_unused:UNUSED_PAD src0_sel:DWORD src1_sel:WORD_1
	v_add3_u32 v59, v82, v59, s56
	ds_write_b64 v75, v[62:63]
	ds_write_b16_d16_hi v76, v59 offset:4096
	v_bfe_u32 v59, v64, 16, 1
	v_add3_u32 v59, v64, v59, s56
	ds_write_b16_d16_hi v76, v59 offset:4352
	v_bfe_u32 v59, v83, 16, 1
	v_add3_u32 v59, v83, v59, s56
	ds_write_b16_d16_hi v76, v59 offset:4160
	v_bfe_u32 v59, v65, 16, 1
	v_add3_u32 v59, v65, v59, s56
	ds_write_b16_d16_hi v76, v59 offset:4416
	v_bfe_u32 v59, v84, 16, 1
	v_add3_u32 v59, v84, v59, s56
	ds_write_b16_d16_hi v76, v59 offset:4224
	v_bfe_u32 v59, v66, 16, 1
	v_add3_u32 v59, v66, v59, s56
	ds_write_b16_d16_hi v76, v59 offset:4480
	v_bfe_u32 v59, v85, 16, 1
	v_add3_u32 v59, v85, v59, s56
	ds_write_b16_d16_hi v76, v59 offset:4288
	v_bfe_u32 v59, v67, 16, 1
	v_add3_u32 v59, v67, v59, s56
	v_add_u32_e32 v66, s3, v73
	s_mov_b64 s[2:3], -1
	ds_write_b16_d16_hi v76, v59 offset:4544
	s_waitcnt lgkmcnt(0)
	s_barrier
	s_cbranch_scc0 .LBB0_445
	v_ashrrev_i32_e32 v67, 31, v66
	v_lshl_add_u64 v[62:63], v[66:67], 0, v[54:55]
	v_lshlrev_b64 v[64:65], 9, v[62:63]
	v_readlane_b32 s68, v253, 56
	v_lshl_or_b32 v64, v52, 2, v64
	v_readlane_b32 s74, v253, 62
	v_readlane_b32 s75, v253, 63
	v_readlane_b32 s76, v254, 0
	v_readlane_b32 s77, v254, 1
	v_readlane_b32 s69, v253, 57
	v_readlane_b32 s70, v253, 58
	v_readlane_b32 s71, v253, 59
	v_readlane_b32 s72, v253, 60
	v_readlane_b32 s73, v253, 61
	v_readlane_b32 s78, v254, 2
	v_readlane_b32 s79, v254, 3
	v_readlane_b32 s80, v254, 4
	v_readlane_b32 s81, v254, 5
	v_readlane_b32 s82, v254, 6
	v_readlane_b32 s83, v254, 7
	v_lshl_add_u64 v[62:63], s[74:75], 0, v[64:65]
	v_lshl_add_u64 v[64:65], s[76:77], 0, v[64:65]
	s_mov_b64 s[2:3], 0
